# dn_prep stage 3 waves 4-7: kd^T transpose de-serialised (32 LDS reads in flight, immediate offsets, no 64-bit address mads)
# speedup vs baseline: 1.0171x; 1.0030x over previous
; #define LAS __attribute__((address_space(3)))
; __device__ __forceinline__ float bf2f(unsigned short v) { return __uint_as_float(((unsigned)v) << 16); }
; __device__ __forceinline__ unsigned pk2(float lo, float hi) { const f32x2_t v = {lo, hi}; const bf16x2_t b = __builtin_convertvector(v, bf16x2_t); return __builtin_bit_cast(unsigned, b); }
; __device__ __forceinline__ void dn_prep_item(const Args& a, LAS unsigned char* lds, int item, int tid, int wave, int lane, int& cwh, int next_item) {
;     ...
;         const int t2 = tid - 256; const float gl = gcs[63];
; #pragma unroll 4
;         for (int r = 0; r < 32; ++r) { const int idx = t2 + 256 * r, i = idx & 63, d = idx >> 6;
;             const float v = bf2f(*(const LAS unsigned short*)(lds + L_KH + i * KS_ + 2 * d)) * __expf(gl - gcs[i]);
;             *(LAS unsigned short*)(lds + L_KDT + d * AS_ + 2 * i) = (unsigned short)(pk2(v, 0.f) & 0xffffu); }
;         if (next_item >= 0) { const int h2 = next_item & 3, n2 = (next_item >> 2) & (NCH - 1), b2 = next_item >> 9; unsigned d0 = 0u, d1 = 0u;
;             const unsigned char* pb = (const unsigned char*)(P + (size_t)(b2 * T + n2 * 64) * NIN + 1024 + h2 * 128);
;             { const int idx = t2, row = idx / 6, seg = idx % 6; if (n2 > 0 || row >= 3) asm volatile("global_load_dword %0, %1, off" : "+v"(d0) : "v"(pb + (ptrdiff_t)(row - 3) * (NIN * 2) + (seg >> 1) * 1024 + (seg & 1) * 128) : "memory"); }
;             { const int idx = t2 + 256, row = idx / 6, seg = idx % 6; if (idx < 402) asm volatile("global_load_dword %0, %1, off" : "+v"(d1) : "v"(pb + (ptrdiff_t)(row - 3) * (NIN * 2) + (seg >> 1) * 1024 + (seg & 1) * 128) : "memory"); }
.LBB0_870:
	v_add_u32_e32 v122, 0xffffff00, v206
	v_ashrrev_i32_e32 v122, 6, v122
	v_lshl_add_u32 v120, v122, 1, v187
	v_mad_u32_u24 v121, v122, s24, v48
	ds_read_u16 v88, v120
	ds_read_u16 v89, v120 offset:8
	ds_read_u16 v90, v120 offset:16
	ds_read_u16 v91, v120 offset:24
	ds_read_u16 v92, v120 offset:32
	ds_read_u16 v93, v120 offset:40
	ds_read_u16 v94, v120 offset:48
	ds_read_u16 v95, v120 offset:56
	ds_read_u16 v96, v120 offset:64
	ds_read_u16 v97, v120 offset:72
	ds_read_u16 v98, v120 offset:80
	ds_read_u16 v99, v120 offset:88
	ds_read_u16 v100, v120 offset:96
	ds_read_u16 v101, v120 offset:104
	ds_read_u16 v102, v120 offset:112
	ds_read_u16 v103, v120 offset:120
	ds_read_u16 v104, v120 offset:128
	ds_read_u16 v105, v120 offset:136
	ds_read_u16 v106, v120 offset:144
	ds_read_u16 v107, v120 offset:152
	ds_read_u16 v108, v120 offset:160
	ds_read_u16 v109, v120 offset:168
	ds_read_u16 v110, v120 offset:176
	ds_read_u16 v111, v120 offset:184
	ds_read_u16 v112, v120 offset:192
	ds_read_u16 v113, v120 offset:200
	ds_read_u16 v114, v120 offset:208
	ds_read_u16 v115, v120 offset:216
	ds_read_u16 v116, v120 offset:224
	ds_read_u16 v117, v120 offset:232
	ds_read_u16 v118, v120 offset:240
	ds_read_u16 v119, v120 offset:248
	s_waitcnt lgkmcnt(0)
	v_lshlrev_b32_e32 v88, 16, v88
	v_mul_f32_e32 v88, v0, v88
	v_cvt_pk_bf16_f32 v88, v88, s0
	v_lshlrev_b32_e32 v89, 16, v89
	v_mul_f32_e32 v89, v0, v89
	v_cvt_pk_bf16_f32 v89, v89, s0
	v_lshlrev_b32_e32 v90, 16, v90
	v_mul_f32_e32 v90, v0, v90
	v_cvt_pk_bf16_f32 v90, v90, s0
	v_lshlrev_b32_e32 v91, 16, v91
	v_mul_f32_e32 v91, v0, v91
	v_cvt_pk_bf16_f32 v91, v91, s0
	v_lshlrev_b32_e32 v92, 16, v92
	v_mul_f32_e32 v92, v0, v92
	v_cvt_pk_bf16_f32 v92, v92, s0
	v_lshlrev_b32_e32 v93, 16, v93
	v_mul_f32_e32 v93, v0, v93
	v_cvt_pk_bf16_f32 v93, v93, s0
	v_lshlrev_b32_e32 v94, 16, v94
	v_mul_f32_e32 v94, v0, v94
	v_cvt_pk_bf16_f32 v94, v94, s0
	v_lshlrev_b32_e32 v95, 16, v95
	v_mul_f32_e32 v95, v0, v95
	v_cvt_pk_bf16_f32 v95, v95, s0
	v_lshlrev_b32_e32 v96, 16, v96
	v_mul_f32_e32 v96, v0, v96
	v_cvt_pk_bf16_f32 v96, v96, s0
	v_lshlrev_b32_e32 v97, 16, v97
	v_mul_f32_e32 v97, v0, v97
	v_cvt_pk_bf16_f32 v97, v97, s0
	v_lshlrev_b32_e32 v98, 16, v98
	v_mul_f32_e32 v98, v0, v98
	v_cvt_pk_bf16_f32 v98, v98, s0
	v_lshlrev_b32_e32 v99, 16, v99
	v_mul_f32_e32 v99, v0, v99
	v_cvt_pk_bf16_f32 v99, v99, s0
	v_lshlrev_b32_e32 v100, 16, v100
	v_mul_f32_e32 v100, v0, v100
	v_cvt_pk_bf16_f32 v100, v100, s0
	v_lshlrev_b32_e32 v101, 16, v101
	v_mul_f32_e32 v101, v0, v101
	v_cvt_pk_bf16_f32 v101, v101, s0
	v_lshlrev_b32_e32 v102, 16, v102
	v_mul_f32_e32 v102, v0, v102
	v_cvt_pk_bf16_f32 v102, v102, s0
	v_lshlrev_b32_e32 v103, 16, v103
	v_mul_f32_e32 v103, v0, v103
	v_cvt_pk_bf16_f32 v103, v103, s0
	v_lshlrev_b32_e32 v104, 16, v104
	v_mul_f32_e32 v104, v0, v104
	v_cvt_pk_bf16_f32 v104, v104, s0
	v_lshlrev_b32_e32 v105, 16, v105
	v_mul_f32_e32 v105, v0, v105
	v_cvt_pk_bf16_f32 v105, v105, s0
	v_lshlrev_b32_e32 v106, 16, v106
	v_mul_f32_e32 v106, v0, v106
	v_cvt_pk_bf16_f32 v106, v106, s0
	v_lshlrev_b32_e32 v107, 16, v107
	v_mul_f32_e32 v107, v0, v107
	v_cvt_pk_bf16_f32 v107, v107, s0
	v_lshlrev_b32_e32 v108, 16, v108
	v_mul_f32_e32 v108, v0, v108
	v_cvt_pk_bf16_f32 v108, v108, s0
	v_lshlrev_b32_e32 v109, 16, v109
	v_mul_f32_e32 v109, v0, v109
	v_cvt_pk_bf16_f32 v109, v109, s0
	v_lshlrev_b32_e32 v110, 16, v110
	v_mul_f32_e32 v110, v0, v110
	v_cvt_pk_bf16_f32 v110, v110, s0
	v_lshlrev_b32_e32 v111, 16, v111
	v_mul_f32_e32 v111, v0, v111
	v_cvt_pk_bf16_f32 v111, v111, s0
	v_lshlrev_b32_e32 v112, 16, v112
	v_mul_f32_e32 v112, v0, v112
	v_cvt_pk_bf16_f32 v112, v112, s0
	v_lshlrev_b32_e32 v113, 16, v113
	v_mul_f32_e32 v113, v0, v113
	v_cvt_pk_bf16_f32 v113, v113, s0
	v_lshlrev_b32_e32 v114, 16, v114
	v_mul_f32_e32 v114, v0, v114
	v_cvt_pk_bf16_f32 v114, v114, s0
	v_lshlrev_b32_e32 v115, 16, v115
	v_mul_f32_e32 v115, v0, v115
	v_cvt_pk_bf16_f32 v115, v115, s0
	v_lshlrev_b32_e32 v116, 16, v116
	v_mul_f32_e32 v116, v0, v116
	v_cvt_pk_bf16_f32 v116, v116, s0
	v_lshlrev_b32_e32 v117, 16, v117
	v_mul_f32_e32 v117, v0, v117
	v_cvt_pk_bf16_f32 v117, v117, s0
	v_lshlrev_b32_e32 v118, 16, v118
	v_mul_f32_e32 v118, v0, v118
	v_cvt_pk_bf16_f32 v118, v118, s0
	v_lshlrev_b32_e32 v119, 16, v119
	v_mul_f32_e32 v119, v0, v119
	v_cvt_pk_bf16_f32 v119, v119, s0
	ds_write_b16 v121, v88
	ds_write_b16 v121, v89 offset:576
	ds_write_b16 v121, v90 offset:1152
	ds_write_b16 v121, v91 offset:1728
	ds_write_b16 v121, v92 offset:2304
	ds_write_b16 v121, v93 offset:2880
	ds_write_b16 v121, v94 offset:3456
	ds_write_b16 v121, v95 offset:4032
	ds_write_b16 v121, v96 offset:4608
	ds_write_b16 v121, v97 offset:5184
	ds_write_b16 v121, v98 offset:5760
	ds_write_b16 v121, v99 offset:6336
	ds_write_b16 v121, v100 offset:6912
	ds_write_b16 v121, v101 offset:7488
	ds_write_b16 v121, v102 offset:8064
	ds_write_b16 v121, v103 offset:8640
	ds_write_b16 v121, v104 offset:9216
	ds_write_b16 v121, v105 offset:9792
	ds_write_b16 v121, v106 offset:10368
	ds_write_b16 v121, v107 offset:10944
	ds_write_b16 v121, v108 offset:11520
	ds_write_b16 v121, v109 offset:12096
	ds_write_b16 v121, v110 offset:12672
	ds_write_b16 v121, v111 offset:13248
	ds_write_b16 v121, v112 offset:13824
	ds_write_b16 v121, v113 offset:14400
	ds_write_b16 v121, v114 offset:14976
	ds_write_b16 v121, v115 offset:15552
	ds_write_b16 v121, v116 offset:16128
	ds_write_b16 v121, v117 offset:16704
	ds_write_b16 v121, v118 offset:17280
	ds_write_b16 v121, v119 offset:17856
	s_cmp_gt_i32 s38, -1
	s_cbranch_scc0 .LBB0_877
	s_bfe_u32 s41, s38, 0x70002
	s_lshl_b32 s22, s38, 4
	s_and_b32 s22, s22, 0x7fffe000
	s_lshl_b32 s23, s41, 6
	s_or_b32 s22, s23, s22
	s_mul_hi_u32 s23, s22, 0x1800
	s_mulk_i32 s22, 0x1800
	s_add_u32 s22, s10, s22
	s_addc_u32 s23, s11, s23
	s_lshl_b32 s42, s38, 8
	s_and_b32 s42, s42, 0x300
	s_add_u32 s22, s22, s42
	s_addc_u32 s23, s23, 0
	s_cmp_lg_u32 s41, 0
	v_readlane_b32 s86, v244, 49
	s_cselect_b64 s[42:43], -1, 0
	v_readlane_b32 s87, v244, 50
	s_or_b64 s[42:43], s[42:43], s[86:87]
	v_mov_b32_e32 v0, 0
	v_mov_b32_e32 v1, 0
	s_and_saveexec_b64 s[86:87], s[42:43]
	s_cbranch_execz .LBB0_874
	v_lshl_add_u64 v[2:3], s[22:23], 0, v[50:51]
	v_lshl_add_u64 v[2:3], v[2:3], 0, v[52:53]
	s_movk_i32 s42, 0xc000
	v_lshl_add_u64 v[2:3], v[2:3], 0, v[54:55]
	s_mov_b32 s43, -1
	v_mov_b32_e32 v1, v57
	v_lshl_add_u64 v[2:3], v[2:3], 0, s[42:43]
	global_load_dword v1, v[2:3], off
